# ret_core epilogue: L2-prefetch touches for the silu(g) lines of row groups 2-4 issued before group 1 loads (plus LayerNorm and swa_attn load/wait restructuring)
# speedup vs baseline: 1.0458x; 1.0458x over previous
.LBB0_1800:
	s_or_b64 exec, exec, s[8:9]
	s_waitcnt lgkmcnt(0)
	s_barrier
	s_ashr_i32 s0, s18, 2
	s_lshl_b32 s2, s0, 10
	s_lshl_b32 s0, s0, 6
	v_and_b32_e32 v128, 15, v169
	s_add_i32 s0, s0, s42
	s_add_i32 s2, s2, 0
	v_or_b32_e32 v140, s0, v128
	s_lshl_b32 s0, s34, 2
	s_add_u32 s16, s10, s0
	s_addc_u32 s17, s27, 0
	v_ashrrev_i32_e32 v141, 31, v140
	s_lshl_b32 s3, s18, 6
	v_lshrrev_b32_e32 v134, 2, v169
	v_lshlrev_b64 v[132:133], 13, v[140:141]
	s_lshl_b32 s0, s34, 1
	s_and_b32 s3, s3, 0xc0
	v_or_b32_e32 v132, s0, v132
	v_and_or_b32 v134, v134, 12, s3
	v_lshl_add_u64 v[130:131], s[36:37], 0, v[132:133]
	v_lshlrev_b32_e32 v224, 1, v134
	v_lshl_add_u64 v[170:171], v[130:131], 0, v[224:225]
	s_mov_b32 s100, 0x20000
	s_mov_b32 s101, 0
	v_lshl_add_u64 v[196:197], v[170:171], 0, s[100:101]
	global_load_dword v198, v[196:197], off
	global_load_dword v198, v[196:197], off offset:512
	v_lshl_add_u64 v[196:197], v[196:197], 0, s[100:101]
	global_load_dword v198, v[196:197], off
	global_load_dword v198, v[196:197], off offset:512
	v_lshl_add_u64 v[196:197], v[196:197], 0, s[100:101]
	global_load_dword v198, v[196:197], off
	global_load_dword v198, v[196:197], off offset:512
	global_load_dwordx2 v[172:173], v[170:171], off
	v_lshlrev_b32_e32 v141, 2, v134
	global_load_dwordx4 v[148:151], v141, s[16:17]
	global_load_dwordx2 v[174:175], v[170:171], off offset:32
	global_load_dwordx4 v[152:155], v141, s[16:17] offset:64
	global_load_dwordx2 v[180:181], v[170:171], off offset:64
	v_mul_f32_e32 v142, 0x3b000000, v129
	v_lshl_add_u32 v146, v128, 4, s2
	v_pk_add_f32 v[176:177], v[124:125], v[142:143] op_sel_hi:[1,0] neg_lo:[0,1] neg_hi:[0,1]
	v_add_u32_e32 v124, 0x11000, v146
	v_add_u32_e32 v125, 0x11100, v146
	v_pk_add_f32 v[178:179], v[126:127], v[142:143] op_sel_hi:[1,0] neg_lo:[0,1] neg_hi:[0,1]
	ds_read_b128 v[128:131], v124
	ds_read_b128 v[124:127], v125
	global_load_dwordx4 v[156:159], v141, s[16:17] offset:128
	global_load_dwordx4 v[160:163], v141, s[16:17] offset:192
	global_load_dwordx4 v[164:167], v141, s[16:17] offset:1024
	global_load_dwordx4 v[136:139], v141, s[16:17] offset:1088
	global_load_dwordx2 v[184:185], v[170:171], off offset:96
	v_lshl_add_u64 v[182:183], s[40:41], 0, v[132:133]
	v_pk_add_f32 v[120:121], v[120:121], v[142:143] op_sel_hi:[1,0] neg_lo:[0,1] neg_hi:[0,1]
	s_waitcnt lgkmcnt(1)
	v_mov_b32_e32 v132, v129
	v_mov_b32_e32 v133, v130
	v_mov_b32_e32 v129, v131
	v_pk_add_f32 v[128:129], v[132:133], v[128:129]
	v_pk_add_f32 v[122:123], v[122:123], v[142:143] op_sel_hi:[1,0] neg_lo:[0,1] neg_hi:[0,1]
	v_add_f32_e32 v128, v128, v129
	v_fmamk_f32 v128, v128, 0x3b000000, v245
	v_mul_f32_e32 v129, 0x4f800000, v128
	v_cmp_gt_f32_e32 vcc, s87, v128
	v_pk_add_f32 v[116:117], v[116:117], v[142:143] op_sel_hi:[1,0] neg_lo:[0,1] neg_hi:[0,1]
	v_pk_add_f32 v[118:119], v[118:119], v[142:143] op_sel_hi:[1,0] neg_lo:[0,1] neg_hi:[0,1]
	v_cndmask_b32_e32 v147, v128, v129, vcc
	global_load_dwordx4 v[132:135], v141, s[16:17] offset:1152
	global_load_dwordx4 v[128:131], v141, s[16:17] offset:1216
	global_load_dwordx2 v[186:187], v[170:171], off offset:512
	v_sqrt_f32_e32 v168, v147
	v_pk_add_f32 v[108:109], v[108:109], v[142:143] op_sel_hi:[1,0] neg_lo:[0,1] neg_hi:[0,1]
	v_pk_add_f32 v[110:111], v[110:111], v[142:143] op_sel_hi:[1,0] neg_lo:[0,1] neg_hi:[0,1]
	v_pk_add_f32 v[104:105], v[104:105], v[142:143] op_sel_hi:[1,0] neg_lo:[0,1] neg_hi:[0,1]
	v_add_u32_e32 v188, -1, v168
	v_add_u32_e32 v189, 1, v168
	v_fma_f32 v190, -v188, v168, v147
	v_fma_f32 v191, -v189, v168, v147
	v_cmp_ge_f32_e64 s[38:39], 0, v190
	v_pk_add_f32 v[106:107], v[106:107], v[142:143] op_sel_hi:[1,0] neg_lo:[0,1] neg_hi:[0,1]
	v_pk_add_f32 v[100:101], v[100:101], v[142:143] op_sel_hi:[1,0] neg_lo:[0,1] neg_hi:[0,1]
	v_cndmask_b32_e64 v168, v168, v188, s[38:39]
	v_cmp_lt_f32_e64 s[38:39], 0, v191
	v_pk_add_f32 v[102:103], v[102:103], v[142:143] op_sel_hi:[1,0] neg_lo:[0,1] neg_hi:[0,1]
	v_pk_add_f32 v[96:97], v[96:97], v[142:143] op_sel_hi:[1,0] neg_lo:[0,1] neg_hi:[0,1]
	v_cndmask_b32_e64 v168, v168, v189, s[38:39]
	v_mul_f32_e32 v188, 0x37800000, v168
	v_cndmask_b32_e32 v168, v168, v188, vcc
	global_load_dwordx2 v[188:189], v[170:171], off offset:544
	global_load_dwordx2 v[190:191], v[170:171], off offset:576
	s_nop 0
	global_load_dwordx2 v[170:171], v[170:171], off offset:608
	v_cmp_class_f32_e32 vcc, v147, v243
	v_pk_add_f32 v[98:99], v[98:99], v[142:143] op_sel_hi:[1,0] neg_lo:[0,1] neg_hi:[0,1]
	s_add_i32 s29, s29, s94
	v_cndmask_b32_e32 v147, v168, v147, vcc
	v_div_scale_f32 v168, s[2:3], v147, v147, 1.0
	v_rcp_f32_e32 v192, v168
	v_div_scale_f32 v193, vcc, 1.0, v147, 1.0
	s_add_i32 s28, s28, s66
	v_fma_f32 v194, -v168, v192, 1.0
	v_fmac_f32_e32 v192, v194, v192
	v_mul_f32_e32 v194, v193, v192
	v_fma_f32 v195, -v168, v194, v193
	v_fmac_f32_e32 v194, v195, v192
	v_fma_f32 v168, -v168, v194, v193
	v_div_fmas_f32 v168, v168, v192, v194
	v_div_fixup_f32 v168, v168, v147, 1.0
	v_pk_mul_f32 v[176:177], v[176:177], v[168:169] op_sel_hi:[1,0]
	v_pk_mul_f32 v[178:179], v[178:179], v[168:169] op_sel_hi:[1,0]
	v_pk_mul_f32 v[120:121], v[120:121], v[168:169] op_sel_hi:[1,0]
	v_pk_mul_f32 v[122:123], v[122:123], v[168:169] op_sel_hi:[1,0]
	v_pk_mul_f32 v[116:117], v[116:117], v[168:169] op_sel_hi:[1,0]
	v_pk_mul_f32 v[118:119], v[118:119], v[168:169] op_sel_hi:[1,0]
	v_pk_mul_f32 v[108:109], v[108:109], v[168:169] op_sel_hi:[1,0]
	v_pk_mul_f32 v[110:111], v[110:111], v[168:169] op_sel_hi:[1,0]
	v_pk_mul_f32 v[104:105], v[104:105], v[168:169] op_sel_hi:[1,0]
	v_pk_mul_f32 v[106:107], v[106:107], v[168:169] op_sel_hi:[1,0]
	v_pk_mul_f32 v[100:101], v[100:101], v[168:169] op_sel_hi:[1,0]
	v_pk_mul_f32 v[102:103], v[102:103], v[168:169] op_sel_hi:[1,0]
	v_pk_mul_f32 v[96:97], v[96:97], v[168:169] op_sel_hi:[1,0]
	v_pk_mul_f32 v[98:99], v[98:99], v[168:169] op_sel_hi:[1,0]
	s_cmpk_lt_i32 s29, 0x400
	s_waitcnt vmcnt(15)
	v_cvt_f32_f16_e32 v192, v172
	v_cvt_f32_f16_sdwa v193, v172 dst_sel:DWORD dst_unused:UNUSED_PAD src0_sel:WORD_1
	v_cvt_f32_f16_e32 v172, v173
	v_cvt_f32_f16_sdwa v173, v173 dst_sel:DWORD dst_unused:UNUSED_PAD src0_sel:WORD_1
	s_waitcnt vmcnt(14)
	v_pk_mul_f32 v[148:149], v[148:149], v[176:177]
	v_pk_mul_f32 v[150:151], v[150:151], v[178:179]
	v_pk_mul_f32 v[148:149], v[148:149], v[192:193]
	v_pk_mul_f32 v[150:151], v[150:151], v[172:173]
	v_cvt_pk_bf16_f32 v148, v148, v149
	v_cvt_pk_bf16_f32 v149, v150, v151
	v_lshl_add_u64 v[150:151], v[182:183], 0, v[224:225]
	global_store_dwordx2 v[150:151], v[148:149], off
	s_waitcnt vmcnt(14)
	v_cvt_f32_f16_e32 v148, v174
	v_cvt_f32_f16_sdwa v149, v174 dst_sel:DWORD dst_unused:UNUSED_PAD src0_sel:WORD_1
	s_waitcnt vmcnt(13)
	v_pk_mul_f32 v[120:121], v[152:153], v[120:121]
	v_pk_mul_f32 v[122:123], v[154:155], v[122:123]
	s_waitcnt vmcnt(11)
	v_pk_mul_f32 v[116:117], v[116:117], v[156:157]
	v_pk_mul_f32 v[120:121], v[120:121], v[148:149]
	v_cvt_f32_f16_e32 v148, v175
	v_cvt_f32_f16_sdwa v149, v175 dst_sel:DWORD dst_unused:UNUSED_PAD src0_sel:WORD_1
	v_cvt_pk_bf16_f32 v120, v120, v121
	v_pk_mul_f32 v[118:119], v[118:119], v[158:159]
	s_waitcnt vmcnt(10)
	v_pk_mul_f32 v[108:109], v[108:109], v[160:161]
	v_pk_mul_f32 v[122:123], v[122:123], v[148:149]
	v_pk_mul_f32 v[110:111], v[110:111], v[162:163]
	v_cvt_pk_bf16_f32 v121, v122, v123
	global_store_dwordx2 v[150:151], v[120:121], off offset:32
	v_cvt_f32_f16_e32 v120, v180
	v_cvt_f32_f16_sdwa v121, v180 dst_sel:DWORD dst_unused:UNUSED_PAD src0_sel:WORD_1
	s_waitcnt vmcnt(9)
	v_pk_mul_f32 v[104:105], v[104:105], v[136:137]
	v_pk_mul_f32 v[106:107], v[106:107], v[138:139]
	s_waitcnt vmcnt(7)
	v_pk_mul_f32 v[100:101], v[100:101], v[132:133]
	v_pk_mul_f32 v[116:117], v[116:117], v[120:121]
	v_cvt_f32_f16_e32 v120, v181
	v_cvt_f32_f16_sdwa v121, v181 dst_sel:DWORD dst_unused:UNUSED_PAD src0_sel:WORD_1
	v_cvt_pk_bf16_f32 v116, v116, v117
	v_pk_mul_f32 v[102:103], v[102:103], v[134:135]
	s_waitcnt vmcnt(6)
	v_pk_mul_f32 v[96:97], v[96:97], v[128:129]
	v_pk_mul_f32 v[118:119], v[118:119], v[120:121]
	v_pk_mul_f32 v[98:99], v[98:99], v[130:131]
	v_cvt_pk_bf16_f32 v117, v118, v119
	global_store_dwordx2 v[150:151], v[116:117], off offset:64
	v_cvt_f32_f16_e32 v116, v184
	v_cvt_f32_f16_sdwa v117, v184 dst_sel:DWORD dst_unused:UNUSED_PAD src0_sel:WORD_1
	v_pk_mul_f32 v[108:109], v[108:109], v[116:117]
	v_cvt_f32_f16_e32 v116, v185
	v_cvt_f32_f16_sdwa v117, v185 dst_sel:DWORD dst_unused:UNUSED_PAD src0_sel:WORD_1
	v_cvt_pk_bf16_f32 v108, v108, v109
	v_pk_mul_f32 v[110:111], v[110:111], v[116:117]
	s_nop 0
	v_cvt_pk_bf16_f32 v109, v110, v111
	global_store_dwordx2 v[150:151], v[108:109], off offset:96
	s_waitcnt vmcnt(7)
	v_cvt_f32_f16_e32 v108, v186
	v_cvt_f32_f16_sdwa v109, v186 dst_sel:DWORD dst_unused:UNUSED_PAD src0_sel:WORD_1
	v_pk_add_f32 v[110:111], v[112:113], v[142:143] op_sel_hi:[1,0] neg_lo:[0,1] neg_hi:[0,1]
	v_pk_add_f32 v[112:113], v[114:115], v[142:143] op_sel_hi:[1,0] neg_lo:[0,1] neg_hi:[0,1]
	v_pk_mul_f32 v[110:111], v[110:111], v[168:169] op_sel_hi:[1,0]
	v_pk_mul_f32 v[112:113], v[112:113], v[168:169] op_sel_hi:[1,0]
	v_pk_mul_f32 v[110:111], v[110:111], v[164:165]
	v_pk_mul_f32 v[112:113], v[112:113], v[166:167]
	v_pk_mul_f32 v[108:109], v[110:111], v[108:109]
	v_cvt_f32_f16_e32 v110, v187
	v_cvt_f32_f16_sdwa v111, v187 dst_sel:DWORD dst_unused:UNUSED_PAD src0_sel:WORD_1
	v_cvt_pk_bf16_f32 v108, v108, v109
	v_pk_mul_f32 v[110:111], v[112:113], v[110:111]
	s_nop 0
	v_cvt_pk_bf16_f32 v109, v110, v111
	global_store_dwordx2 v[150:151], v[108:109], off offset:512
	s_waitcnt vmcnt(7)
	v_cvt_f32_f16_e32 v108, v188
	v_cvt_f32_f16_sdwa v109, v188 dst_sel:DWORD dst_unused:UNUSED_PAD src0_sel:WORD_1
	v_pk_mul_f32 v[104:105], v[104:105], v[108:109]
	v_cvt_f32_f16_e32 v108, v189
	v_cvt_f32_f16_sdwa v109, v189 dst_sel:DWORD dst_unused:UNUSED_PAD src0_sel:WORD_1
	v_cvt_pk_bf16_f32 v104, v104, v105
	v_pk_mul_f32 v[106:107], v[106:107], v[108:109]
	s_nop 0
	v_cvt_pk_bf16_f32 v105, v106, v107
	global_store_dwordx2 v[150:151], v[104:105], off offset:544
	s_waitcnt vmcnt(7)
	v_cvt_f32_f16_e32 v104, v190
	v_cvt_f32_f16_sdwa v105, v190 dst_sel:DWORD dst_unused:UNUSED_PAD src0_sel:WORD_1
	v_pk_mul_f32 v[100:101], v[100:101], v[104:105]
	v_cvt_f32_f16_e32 v104, v191
	v_cvt_f32_f16_sdwa v105, v191 dst_sel:DWORD dst_unused:UNUSED_PAD src0_sel:WORD_1
	v_cvt_pk_bf16_f32 v100, v100, v101
	v_pk_mul_f32 v[102:103], v[102:103], v[104:105]
	s_nop 0
	v_cvt_pk_bf16_f32 v101, v102, v103
	global_store_dwordx2 v[150:151], v[100:101], off offset:576
	s_waitcnt vmcnt(7)
	v_cvt_f32_f16_e32 v100, v170
	v_cvt_f32_f16_sdwa v101, v170 dst_sel:DWORD dst_unused:UNUSED_PAD src0_sel:WORD_1
	v_pk_mul_f32 v[96:97], v[96:97], v[100:101]
	v_cvt_f32_f16_e32 v100, v171
	v_cvt_f32_f16_sdwa v101, v171 dst_sel:DWORD dst_unused:UNUSED_PAD src0_sel:WORD_1
	v_cvt_pk_bf16_f32 v96, v96, v97
	v_pk_mul_f32 v[98:99], v[98:99], v[100:101]
	s_nop 0
	v_cvt_pk_bf16_f32 v97, v98, v99
	global_store_dwordx2 v[150:151], v[96:97], off offset:608
	v_or_b32_e32 v96, 16, v140
	v_ashrrev_i32_e32 v97, 31, v96
	v_lshlrev_b64 v[132:133], 13, v[96:97]
	v_or_b32_e32 v132, s0, v132
	v_lshl_add_u64 v[96:97], s[36:37], 0, v[132:133]
	v_lshl_add_u64 v[134:135], v[96:97], 0, v[224:225]
	global_load_dwordx2 v[136:137], v[134:135], off
	global_load_dwordx4 v[100:103], v141, s[16:17]
	global_load_dwordx2 v[138:139], v[134:135], off offset:32
	global_load_dwordx4 v[104:107], v141, s[16:17] offset:64
	s_waitcnt lgkmcnt(0)
	v_mov_b32_e32 v96, v125
	v_mov_b32_e32 v97, v126
	v_mov_b32_e32 v125, v127
	v_pk_add_f32 v[96:97], v[96:97], v[124:125]
	global_load_dwordx2 v[148:149], v[134:135], off offset:64
	global_load_dwordx2 v[150:151], v[134:135], off offset:96
	global_load_dwordx2 v[152:153], v[134:135], off offset:512
	v_add_f32_e32 v96, v96, v97
	v_fmamk_f32 v96, v96, 0x3b000000, v245
	v_mul_f32_e32 v97, 0x4f800000, v96
	v_cmp_gt_f32_e32 vcc, s87, v96
	global_load_dwordx4 v[108:111], v141, s[16:17] offset:128
	global_load_dwordx4 v[112:115], v141, s[16:17] offset:192
	v_cndmask_b32_e32 v96, v96, v97, vcc
	v_sqrt_f32_e32 v97, v96
	v_lshl_add_u64 v[132:133], s[40:41], 0, v[132:133]
	v_add_u32_e32 v98, -1, v97
	v_fma_f32 v99, -v98, v97, v96
	v_cmp_ge_f32_e64 s[38:39], 0, v99
	v_add_u32_e32 v99, 1, v97
	s_waitcnt vmcnt(8)
	v_cvt_f32_f16_e32 v158, v136
	v_cndmask_b32_e64 v98, v97, v98, s[38:39]
	v_fma_f32 v97, -v99, v97, v96
	v_cmp_lt_f32_e64 s[38:39], 0, v97
	v_cvt_f32_f16_sdwa v159, v136 dst_sel:DWORD dst_unused:UNUSED_PAD src0_sel:WORD_1
	s_nop 0
	v_cndmask_b32_e64 v97, v98, v99, s[38:39]
	v_mul_f32_e32 v98, 0x37800000, v97
	v_cndmask_b32_e32 v97, v97, v98, vcc
	v_cmp_class_f32_e32 vcc, v96, v243
	s_nop 1
	v_cndmask_b32_e32 v97, v97, v96, vcc
	v_div_scale_f32 v98, s[2:3], v97, v97, 1.0
	v_rcp_f32_e32 v99, v98
	v_div_scale_f32 v120, vcc, 1.0, v97, 1.0
	v_mul_f32_e32 v96, 0x3b000000, v145
	v_fma_f32 v116, -v98, v99, 1.0
	v_fmac_f32_e32 v99, v116, v99
	global_load_dwordx4 v[116:119], v141, s[16:17] offset:1024
	v_mul_f32_e32 v121, v120, v99
	v_fma_f32 v122, -v98, v121, v120
	v_fmac_f32_e32 v121, v122, v99
	v_fma_f32 v98, -v98, v121, v120
	v_div_fmas_f32 v98, v98, v99, v121
	global_load_dwordx4 v[120:123], v141, s[16:17] offset:1088
	global_load_dwordx4 v[124:127], v141, s[16:17] offset:1152
	global_load_dwordx4 v[128:131], v141, s[16:17] offset:1216
	global_load_dwordx2 v[154:155], v[134:135], off offset:544
	global_load_dwordx2 v[156:157], v[134:135], off offset:576
	s_nop 0
	global_load_dwordx2 v[134:135], v[134:135], off offset:608
	v_div_fixup_f32 v98, v98, v97, 1.0
	v_pk_add_f32 v[40:41], v[40:41], v[96:97] op_sel_hi:[1,0] neg_lo:[0,1] neg_hi:[0,1]
	v_pk_add_f32 v[42:43], v[42:43], v[96:97] op_sel_hi:[1,0] neg_lo:[0,1] neg_hi:[0,1]
	v_pk_mul_f32 v[40:41], v[40:41], v[98:99] op_sel_hi:[1,0]
	v_pk_mul_f32 v[42:43], v[42:43], v[98:99] op_sel_hi:[1,0]
	s_waitcnt vmcnt(14)
	v_pk_mul_f32 v[40:41], v[40:41], v[100:101]
	v_cvt_f32_f16_e32 v100, v137
	v_cvt_f32_f16_sdwa v101, v137 dst_sel:DWORD dst_unused:UNUSED_PAD src0_sel:WORD_1
	v_pk_mul_f32 v[42:43], v[42:43], v[102:103]
	v_pk_mul_f32 v[40:41], v[40:41], v[158:159]
	v_pk_add_f32 v[36:37], v[36:37], v[96:97] op_sel_hi:[1,0] neg_lo:[0,1] neg_hi:[0,1]
	v_pk_mul_f32 v[42:43], v[42:43], v[100:101]
	v_cvt_pk_bf16_f32 v40, v40, v41
	v_cvt_pk_bf16_f32 v41, v42, v43
	v_lshl_add_u64 v[42:43], v[132:133], 0, v[224:225]
	global_store_dwordx2 v[42:43], v[40:41], off
	s_waitcnt vmcnt(14)
	v_cvt_f32_f16_e32 v40, v138
	v_cvt_f32_f16_sdwa v41, v138 dst_sel:DWORD dst_unused:UNUSED_PAD src0_sel:WORD_1
	v_pk_mul_f32 v[36:37], v[36:37], v[98:99] op_sel_hi:[1,0]
	v_pk_add_f32 v[38:39], v[38:39], v[96:97] op_sel_hi:[1,0] neg_lo:[0,1] neg_hi:[0,1]
	s_waitcnt vmcnt(13)
	v_pk_mul_f32 v[36:37], v[36:37], v[104:105]
	v_pk_mul_f32 v[38:39], v[38:39], v[98:99] op_sel_hi:[1,0]
	v_pk_mul_f32 v[36:37], v[36:37], v[40:41]
	v_cvt_f32_f16_e32 v40, v139
	v_cvt_f32_f16_sdwa v41, v139 dst_sel:DWORD dst_unused:UNUSED_PAD src0_sel:WORD_1
	v_pk_mul_f32 v[38:39], v[38:39], v[106:107]
	v_cvt_pk_bf16_f32 v36, v36, v37
	v_pk_add_f32 v[32:33], v[32:33], v[96:97] op_sel_hi:[1,0] neg_lo:[0,1] neg_hi:[0,1]
	v_pk_mul_f32 v[38:39], v[38:39], v[40:41]
	v_pk_mul_f32 v[32:33], v[32:33], v[98:99] op_sel_hi:[1,0]
	v_cvt_pk_bf16_f32 v37, v38, v39
	global_store_dwordx2 v[42:43], v[36:37], off offset:32
	s_waitcnt vmcnt(13)
	v_cvt_f32_f16_e32 v36, v148
	v_cvt_f32_f16_sdwa v37, v148 dst_sel:DWORD dst_unused:UNUSED_PAD src0_sel:WORD_1
	s_waitcnt vmcnt(10)
	v_pk_mul_f32 v[32:33], v[32:33], v[108:109]
	v_pk_add_f32 v[34:35], v[34:35], v[96:97] op_sel_hi:[1,0] neg_lo:[0,1] neg_hi:[0,1]
	v_pk_mul_f32 v[32:33], v[32:33], v[36:37]
	v_cvt_f32_f16_e32 v36, v149
	v_cvt_f32_f16_sdwa v37, v149 dst_sel:DWORD dst_unused:UNUSED_PAD src0_sel:WORD_1
	v_pk_mul_f32 v[34:35], v[34:35], v[98:99] op_sel_hi:[1,0]
	v_cvt_pk_bf16_f32 v32, v32, v33
	v_pk_mul_f32 v[34:35], v[34:35], v[110:111]
	s_nop 0
	v_pk_mul_f32 v[34:35], v[34:35], v[36:37]
	v_pk_add_f32 v[36:37], v[46:47], v[96:97] op_sel_hi:[1,0] neg_lo:[0,1] neg_hi:[0,1]
	v_cvt_pk_bf16_f32 v33, v34, v35
	global_store_dwordx2 v[42:43], v[32:33], off offset:64
	v_cvt_f32_f16_e32 v32, v150
	v_cvt_f32_f16_sdwa v33, v150 dst_sel:DWORD dst_unused:UNUSED_PAD src0_sel:WORD_1
	v_pk_add_f32 v[34:35], v[44:45], v[96:97] op_sel_hi:[1,0] neg_lo:[0,1] neg_hi:[0,1]
	v_pk_mul_f32 v[36:37], v[36:37], v[98:99] op_sel_hi:[1,0]
	v_pk_mul_f32 v[34:35], v[34:35], v[98:99] op_sel_hi:[1,0]
	s_waitcnt vmcnt(10)
	v_pk_mul_f32 v[36:37], v[36:37], v[114:115]
	v_pk_mul_f32 v[34:35], v[34:35], v[112:113]
	s_nop 0
	v_pk_mul_f32 v[32:33], v[34:35], v[32:33]
	v_cvt_f32_f16_e32 v34, v151
	v_cvt_f32_f16_sdwa v35, v151 dst_sel:DWORD dst_unused:UNUSED_PAD src0_sel:WORD_1
	v_cvt_pk_bf16_f32 v32, v32, v33
	v_pk_mul_f32 v[34:35], v[36:37], v[34:35]
	s_nop 0
	v_cvt_pk_bf16_f32 v33, v34, v35
	global_store_dwordx2 v[42:43], v[32:33], off offset:96
	v_cvt_f32_f16_e32 v32, v152
	v_cvt_f32_f16_sdwa v33, v152 dst_sel:DWORD dst_unused:UNUSED_PAD src0_sel:WORD_1
	v_pk_add_f32 v[34:35], v[92:93], v[96:97] op_sel_hi:[1,0] neg_lo:[0,1] neg_hi:[0,1]
	v_pk_add_f32 v[36:37], v[94:95], v[96:97] op_sel_hi:[1,0] neg_lo:[0,1] neg_hi:[0,1]
	v_pk_mul_f32 v[34:35], v[34:35], v[98:99] op_sel_hi:[1,0]
	v_pk_mul_f32 v[36:37], v[36:37], v[98:99] op_sel_hi:[1,0]
	s_waitcnt vmcnt(10)
	v_pk_mul_f32 v[34:35], v[34:35], v[116:117]
	s_nop 0
	v_pk_mul_f32 v[32:33], v[34:35], v[32:33]
	v_cvt_f32_f16_e32 v34, v153
	v_cvt_f32_f16_sdwa v35, v153 dst_sel:DWORD dst_unused:UNUSED_PAD src0_sel:WORD_1
	v_pk_mul_f32 v[36:37], v[36:37], v[118:119]
	v_cvt_pk_bf16_f32 v32, v32, v33
	v_pk_mul_f32 v[34:35], v[36:37], v[34:35]
	s_nop 0
	v_cvt_pk_bf16_f32 v33, v34, v35
	global_store_dwordx2 v[42:43], v[32:33], off offset:512
	s_waitcnt vmcnt(7)
	v_cvt_f32_f16_e32 v32, v154
	v_cvt_f32_f16_sdwa v33, v154 dst_sel:DWORD dst_unused:UNUSED_PAD src0_sel:WORD_1
	v_pk_add_f32 v[34:35], v[88:89], v[96:97] op_sel_hi:[1,0] neg_lo:[0,1] neg_hi:[0,1]
	v_pk_add_f32 v[36:37], v[90:91], v[96:97] op_sel_hi:[1,0] neg_lo:[0,1] neg_hi:[0,1]
	v_pk_mul_f32 v[34:35], v[34:35], v[98:99] op_sel_hi:[1,0]
	v_pk_mul_f32 v[36:37], v[36:37], v[98:99] op_sel_hi:[1,0]
	v_pk_mul_f32 v[34:35], v[34:35], v[120:121]
	v_pk_mul_f32 v[36:37], v[36:37], v[122:123]
	v_pk_mul_f32 v[32:33], v[34:35], v[32:33]
	v_cvt_f32_f16_e32 v34, v155
	v_cvt_f32_f16_sdwa v35, v155 dst_sel:DWORD dst_unused:UNUSED_PAD src0_sel:WORD_1
	v_cvt_pk_bf16_f32 v32, v32, v33
	v_pk_mul_f32 v[34:35], v[36:37], v[34:35]
	s_nop 0
	v_cvt_pk_bf16_f32 v33, v34, v35
	global_store_dwordx2 v[42:43], v[32:33], off offset:544
	s_waitcnt vmcnt(7)
	v_cvt_f32_f16_e32 v32, v156
	v_cvt_f32_f16_sdwa v33, v156 dst_sel:DWORD dst_unused:UNUSED_PAD src0_sel:WORD_1
	v_pk_add_f32 v[34:35], v[84:85], v[96:97] op_sel_hi:[1,0] neg_lo:[0,1] neg_hi:[0,1]
	v_pk_add_f32 v[36:37], v[86:87], v[96:97] op_sel_hi:[1,0] neg_lo:[0,1] neg_hi:[0,1]
	v_pk_mul_f32 v[34:35], v[34:35], v[98:99] op_sel_hi:[1,0]
	v_pk_mul_f32 v[36:37], v[36:37], v[98:99] op_sel_hi:[1,0]
	v_pk_mul_f32 v[34:35], v[34:35], v[124:125]
	v_pk_mul_f32 v[36:37], v[36:37], v[126:127]
	v_pk_mul_f32 v[32:33], v[34:35], v[32:33]
	v_cvt_f32_f16_e32 v34, v157
	v_cvt_f32_f16_sdwa v35, v157 dst_sel:DWORD dst_unused:UNUSED_PAD src0_sel:WORD_1
	v_cvt_pk_bf16_f32 v32, v32, v33
	v_pk_mul_f32 v[34:35], v[36:37], v[34:35]
	s_nop 0
	v_cvt_pk_bf16_f32 v33, v34, v35
	global_store_dwordx2 v[42:43], v[32:33], off offset:576
	s_waitcnt vmcnt(7)
	v_cvt_f32_f16_e32 v32, v134
	v_cvt_f32_f16_sdwa v33, v134 dst_sel:DWORD dst_unused:UNUSED_PAD src0_sel:WORD_1
	v_pk_add_f32 v[34:35], v[80:81], v[96:97] op_sel_hi:[1,0] neg_lo:[0,1] neg_hi:[0,1]
	v_pk_add_f32 v[36:37], v[82:83], v[96:97] op_sel_hi:[1,0] neg_lo:[0,1] neg_hi:[0,1]
	v_pk_mul_f32 v[34:35], v[34:35], v[98:99] op_sel_hi:[1,0]
	v_pk_mul_f32 v[36:37], v[36:37], v[98:99] op_sel_hi:[1,0]
	v_pk_mul_f32 v[34:35], v[34:35], v[128:129]
	v_pk_mul_f32 v[36:37], v[36:37], v[130:131]
	v_pk_mul_f32 v[32:33], v[34:35], v[32:33]
	v_cvt_f32_f16_e32 v34, v135
	v_cvt_f32_f16_sdwa v35, v135 dst_sel:DWORD dst_unused:UNUSED_PAD src0_sel:WORD_1
	v_cvt_pk_bf16_f32 v32, v32, v33
	v_pk_mul_f32 v[34:35], v[36:37], v[34:35]
	s_nop 0
	v_cvt_pk_bf16_f32 v33, v34, v35
	global_store_dwordx2 v[42:43], v[32:33], off offset:608
	v_or_b32_e32 v32, 32, v140
	v_ashrrev_i32_e32 v33, 31, v32
	v_lshlrev_b64 v[104:105], 13, v[32:33]
	v_or_b32_e32 v104, s0, v104
	v_lshl_add_u64 v[32:33], s[36:37], 0, v[104:105]
	v_lshl_add_u64 v[106:107], v[32:33], 0, v[224:225]
	global_load_dwordx2 v[108:109], v[106:107], off
	global_load_dwordx4 v[40:43], v141, s[16:17]
	global_load_dwordx2 v[110:111], v[106:107], off offset:32
	v_add_u32_e32 v32, 0x11200, v146
	ds_read_b128 v[36:39], v32
	global_load_dwordx4 v[44:47], v141, s[16:17] offset:64
	global_load_dwordx2 v[112:113], v[106:107], off offset:64
	global_load_dwordx2 v[114:115], v[106:107], off offset:96
	global_load_dwordx2 v[116:117], v[106:107], off offset:512
	s_waitcnt lgkmcnt(0)
	v_mov_b32_e32 v80, v37
	v_mov_b32_e32 v81, v38
	v_mov_b32_e32 v37, v39
	v_pk_add_f32 v[36:37], v[80:81], v[36:37]
	global_load_dwordx4 v[80:83], v141, s[16:17] offset:128
	v_add_f32_e32 v36, v36, v37
	v_fmamk_f32 v36, v36, 0x3b000000, v245
	v_mul_f32_e32 v37, 0x4f800000, v36
	v_cmp_gt_f32_e32 vcc, s87, v36
	global_load_dwordx4 v[84:87], v141, s[16:17] offset:192
	v_add_u32_e32 v32, 0x11300, v146
	v_cndmask_b32_e32 v36, v36, v37, vcc
	v_sqrt_f32_e32 v37, v36
	ds_read_b128 v[32:35], v32
	v_lshl_add_u64 v[104:105], s[40:41], 0, v[104:105]
	v_add_u32_e32 v38, -1, v37
	v_fma_f32 v39, -v38, v37, v36
	v_cmp_ge_f32_e64 s[38:39], 0, v39
	v_add_u32_e32 v39, 1, v37
	s_waitcnt vmcnt(8)
	v_cvt_f32_f16_e32 v122, v108
	v_cndmask_b32_e64 v38, v37, v38, s[38:39]
	v_fma_f32 v37, -v39, v37, v36
	v_cmp_lt_f32_e64 s[38:39], 0, v37
	v_cvt_f32_f16_sdwa v123, v108 dst_sel:DWORD dst_unused:UNUSED_PAD src0_sel:WORD_1
	s_nop 0
	v_cndmask_b32_e64 v37, v38, v39, s[38:39]
	v_mul_f32_e32 v38, 0x37800000, v37
	v_cndmask_b32_e32 v37, v37, v38, vcc
	v_cmp_class_f32_e32 vcc, v36, v243
	s_nop 1
	v_cndmask_b32_e32 v37, v37, v36, vcc
	v_div_scale_f32 v38, s[2:3], v37, v37, 1.0
	v_rcp_f32_e32 v39, v38
	v_div_scale_f32 v92, vcc, 1.0, v37, 1.0
	v_mul_f32_e32 v36, 0x3b000000, v144
	v_fma_f32 v88, -v38, v39, 1.0
	v_fmac_f32_e32 v39, v88, v39
	global_load_dwordx4 v[88:91], v141, s[16:17] offset:1024
	v_mul_f32_e32 v93, v92, v39
	v_fma_f32 v94, -v38, v93, v92
	v_fmac_f32_e32 v93, v94, v39
	v_fma_f32 v38, -v38, v93, v92
	v_div_fmas_f32 v38, v38, v39, v93
	global_load_dwordx4 v[92:95], v141, s[16:17] offset:1088
	global_load_dwordx4 v[96:99], v141, s[16:17] offset:1152
	global_load_dwordx4 v[100:103], v141, s[16:17] offset:1216
	global_load_dwordx2 v[118:119], v[106:107], off offset:544
	global_load_dwordx2 v[120:121], v[106:107], off offset:576
	s_nop 0
	global_load_dwordx2 v[106:107], v[106:107], off offset:608
	v_div_fixup_f32 v38, v38, v37, 1.0
	v_pk_add_f32 v[24:25], v[24:25], v[36:37] op_sel_hi:[1,0] neg_lo:[0,1] neg_hi:[0,1]
	v_pk_add_f32 v[26:27], v[26:27], v[36:37] op_sel_hi:[1,0] neg_lo:[0,1] neg_hi:[0,1]
	v_pk_mul_f32 v[24:25], v[24:25], v[38:39] op_sel_hi:[1,0]
	v_pk_mul_f32 v[26:27], v[26:27], v[38:39] op_sel_hi:[1,0]
	s_waitcnt vmcnt(14)
	v_pk_mul_f32 v[24:25], v[24:25], v[40:41]
	v_cvt_f32_f16_e32 v40, v109
	v_cvt_f32_f16_sdwa v41, v109 dst_sel:DWORD dst_unused:UNUSED_PAD src0_sel:WORD_1
	v_pk_mul_f32 v[26:27], v[26:27], v[42:43]
	v_pk_mul_f32 v[24:25], v[24:25], v[122:123]
	v_pk_add_f32 v[20:21], v[20:21], v[36:37] op_sel_hi:[1,0] neg_lo:[0,1] neg_hi:[0,1]
	v_pk_mul_f32 v[26:27], v[26:27], v[40:41]
	v_cvt_pk_bf16_f32 v24, v24, v25
	v_cvt_pk_bf16_f32 v25, v26, v27
	v_lshl_add_u64 v[26:27], v[104:105], 0, v[224:225]
	global_store_dwordx2 v[26:27], v[24:25], off
	s_waitcnt vmcnt(14)
	v_cvt_f32_f16_e32 v24, v110
	v_cvt_f32_f16_sdwa v25, v110 dst_sel:DWORD dst_unused:UNUSED_PAD src0_sel:WORD_1
	v_pk_mul_f32 v[20:21], v[20:21], v[38:39] op_sel_hi:[1,0]
	v_pk_add_f32 v[22:23], v[22:23], v[36:37] op_sel_hi:[1,0] neg_lo:[0,1] neg_hi:[0,1]
	s_waitcnt vmcnt(13)
	v_pk_mul_f32 v[20:21], v[20:21], v[44:45]
	v_pk_mul_f32 v[22:23], v[22:23], v[38:39] op_sel_hi:[1,0]
	v_pk_mul_f32 v[20:21], v[20:21], v[24:25]
	v_cvt_f32_f16_e32 v24, v111
	v_cvt_f32_f16_sdwa v25, v111 dst_sel:DWORD dst_unused:UNUSED_PAD src0_sel:WORD_1
	v_pk_mul_f32 v[22:23], v[22:23], v[46:47]
	v_cvt_pk_bf16_f32 v20, v20, v21
	v_pk_add_f32 v[16:17], v[16:17], v[36:37] op_sel_hi:[1,0] neg_lo:[0,1] neg_hi:[0,1]
	v_pk_mul_f32 v[22:23], v[22:23], v[24:25]
	v_pk_mul_f32 v[16:17], v[16:17], v[38:39] op_sel_hi:[1,0]
	v_cvt_pk_bf16_f32 v21, v22, v23
	global_store_dwordx2 v[26:27], v[20:21], off offset:32
	s_waitcnt vmcnt(13)
	v_cvt_f32_f16_e32 v20, v112
	v_cvt_f32_f16_sdwa v21, v112 dst_sel:DWORD dst_unused:UNUSED_PAD src0_sel:WORD_1
	s_waitcnt vmcnt(10)
	v_pk_mul_f32 v[16:17], v[16:17], v[80:81]
	v_pk_add_f32 v[18:19], v[18:19], v[36:37] op_sel_hi:[1,0] neg_lo:[0,1] neg_hi:[0,1]
	v_pk_mul_f32 v[16:17], v[16:17], v[20:21]
	v_cvt_f32_f16_e32 v20, v113
	v_cvt_f32_f16_sdwa v21, v113 dst_sel:DWORD dst_unused:UNUSED_PAD src0_sel:WORD_1
	v_pk_mul_f32 v[18:19], v[18:19], v[38:39] op_sel_hi:[1,0]
	v_cvt_pk_bf16_f32 v16, v16, v17
	v_pk_mul_f32 v[18:19], v[18:19], v[82:83]
	s_nop 0
	v_pk_mul_f32 v[18:19], v[18:19], v[20:21]
	v_pk_add_f32 v[20:21], v[30:31], v[36:37] op_sel_hi:[1,0] neg_lo:[0,1] neg_hi:[0,1]
	v_cvt_pk_bf16_f32 v17, v18, v19
	global_store_dwordx2 v[26:27], v[16:17], off offset:64
	v_cvt_f32_f16_e32 v16, v114
	v_cvt_f32_f16_sdwa v17, v114 dst_sel:DWORD dst_unused:UNUSED_PAD src0_sel:WORD_1
	v_pk_add_f32 v[18:19], v[28:29], v[36:37] op_sel_hi:[1,0] neg_lo:[0,1] neg_hi:[0,1]
	v_pk_mul_f32 v[20:21], v[20:21], v[38:39] op_sel_hi:[1,0]
	v_pk_mul_f32 v[18:19], v[18:19], v[38:39] op_sel_hi:[1,0]
	s_waitcnt vmcnt(10)
	v_pk_mul_f32 v[20:21], v[20:21], v[86:87]
	v_pk_mul_f32 v[18:19], v[18:19], v[84:85]
	s_nop 0
	v_pk_mul_f32 v[16:17], v[18:19], v[16:17]
	v_cvt_f32_f16_e32 v18, v115
	v_cvt_f32_f16_sdwa v19, v115 dst_sel:DWORD dst_unused:UNUSED_PAD src0_sel:WORD_1
	v_cvt_pk_bf16_f32 v16, v16, v17
	v_pk_mul_f32 v[18:19], v[20:21], v[18:19]
	s_nop 0
	v_cvt_pk_bf16_f32 v17, v18, v19
	global_store_dwordx2 v[26:27], v[16:17], off offset:96
	v_cvt_f32_f16_e32 v16, v116
	v_cvt_f32_f16_sdwa v17, v116 dst_sel:DWORD dst_unused:UNUSED_PAD src0_sel:WORD_1
	v_pk_add_f32 v[18:19], v[76:77], v[36:37] op_sel_hi:[1,0] neg_lo:[0,1] neg_hi:[0,1]
	v_pk_add_f32 v[20:21], v[78:79], v[36:37] op_sel_hi:[1,0] neg_lo:[0,1] neg_hi:[0,1]
	v_pk_mul_f32 v[18:19], v[18:19], v[38:39] op_sel_hi:[1,0]
	v_pk_mul_f32 v[20:21], v[20:21], v[38:39] op_sel_hi:[1,0]
	s_waitcnt vmcnt(10)
	v_pk_mul_f32 v[18:19], v[18:19], v[88:89]
	s_nop 0
	v_pk_mul_f32 v[16:17], v[18:19], v[16:17]
	v_cvt_f32_f16_e32 v18, v117
	v_cvt_f32_f16_sdwa v19, v117 dst_sel:DWORD dst_unused:UNUSED_PAD src0_sel:WORD_1
	v_pk_mul_f32 v[20:21], v[20:21], v[90:91]
	v_cvt_pk_bf16_f32 v16, v16, v17
	v_pk_mul_f32 v[18:19], v[20:21], v[18:19]
	s_nop 0
	v_cvt_pk_bf16_f32 v17, v18, v19
	global_store_dwordx2 v[26:27], v[16:17], off offset:512
	s_waitcnt vmcnt(7)
	v_cvt_f32_f16_e32 v16, v118
	v_cvt_f32_f16_sdwa v17, v118 dst_sel:DWORD dst_unused:UNUSED_PAD src0_sel:WORD_1
	v_pk_add_f32 v[18:19], v[72:73], v[36:37] op_sel_hi:[1,0] neg_lo:[0,1] neg_hi:[0,1]
	v_pk_add_f32 v[20:21], v[74:75], v[36:37] op_sel_hi:[1,0] neg_lo:[0,1] neg_hi:[0,1]
	v_pk_mul_f32 v[18:19], v[18:19], v[38:39] op_sel_hi:[1,0]
	v_pk_mul_f32 v[20:21], v[20:21], v[38:39] op_sel_hi:[1,0]
	v_pk_mul_f32 v[18:19], v[18:19], v[92:93]
	v_pk_mul_f32 v[20:21], v[20:21], v[94:95]
	v_pk_mul_f32 v[16:17], v[18:19], v[16:17]
	v_cvt_f32_f16_e32 v18, v119
	v_cvt_f32_f16_sdwa v19, v119 dst_sel:DWORD dst_unused:UNUSED_PAD src0_sel:WORD_1
	v_cvt_pk_bf16_f32 v16, v16, v17
	v_pk_mul_f32 v[18:19], v[20:21], v[18:19]
	s_nop 0
	v_cvt_pk_bf16_f32 v17, v18, v19
	global_store_dwordx2 v[26:27], v[16:17], off offset:544
	s_waitcnt vmcnt(7)
	v_cvt_f32_f16_e32 v16, v120
	v_cvt_f32_f16_sdwa v17, v120 dst_sel:DWORD dst_unused:UNUSED_PAD src0_sel:WORD_1
	v_pk_add_f32 v[18:19], v[68:69], v[36:37] op_sel_hi:[1,0] neg_lo:[0,1] neg_hi:[0,1]
	v_pk_add_f32 v[20:21], v[70:71], v[36:37] op_sel_hi:[1,0] neg_lo:[0,1] neg_hi:[0,1]
	v_pk_mul_f32 v[18:19], v[18:19], v[38:39] op_sel_hi:[1,0]
	v_pk_mul_f32 v[20:21], v[20:21], v[38:39] op_sel_hi:[1,0]
	v_pk_mul_f32 v[18:19], v[18:19], v[96:97]
	v_pk_mul_f32 v[20:21], v[20:21], v[98:99]
	v_pk_mul_f32 v[16:17], v[18:19], v[16:17]
	v_cvt_f32_f16_e32 v18, v121
	v_cvt_f32_f16_sdwa v19, v121 dst_sel:DWORD dst_unused:UNUSED_PAD src0_sel:WORD_1
	v_cvt_pk_bf16_f32 v16, v16, v17
	v_pk_mul_f32 v[18:19], v[20:21], v[18:19]
	s_nop 0
	v_cvt_pk_bf16_f32 v17, v18, v19
	global_store_dwordx2 v[26:27], v[16:17], off offset:576
	s_waitcnt vmcnt(7)
	v_cvt_f32_f16_e32 v16, v106
	v_cvt_f32_f16_sdwa v17, v106 dst_sel:DWORD dst_unused:UNUSED_PAD src0_sel:WORD_1
	v_pk_add_f32 v[18:19], v[64:65], v[36:37] op_sel_hi:[1,0] neg_lo:[0,1] neg_hi:[0,1]
	v_pk_add_f32 v[20:21], v[66:67], v[36:37] op_sel_hi:[1,0] neg_lo:[0,1] neg_hi:[0,1]
	v_pk_mul_f32 v[18:19], v[18:19], v[38:39] op_sel_hi:[1,0]
	v_pk_mul_f32 v[20:21], v[20:21], v[38:39] op_sel_hi:[1,0]
	v_pk_mul_f32 v[18:19], v[18:19], v[100:101]
	v_pk_mul_f32 v[20:21], v[20:21], v[102:103]
	v_pk_mul_f32 v[16:17], v[18:19], v[16:17]
	v_cvt_f32_f16_e32 v18, v107
	v_cvt_f32_f16_sdwa v19, v107 dst_sel:DWORD dst_unused:UNUSED_PAD src0_sel:WORD_1
	v_cvt_pk_bf16_f32 v16, v16, v17
	v_pk_mul_f32 v[18:19], v[20:21], v[18:19]
	s_nop 0
	v_cvt_pk_bf16_f32 v17, v18, v19
	global_store_dwordx2 v[26:27], v[16:17], off offset:608
	v_or_b32_e32 v16, 48, v140
	v_ashrrev_i32_e32 v17, 31, v16
	v_lshlrev_b64 v[68:69], 13, v[16:17]
	v_or_b32_e32 v68, s0, v68
	v_lshl_add_u64 v[16:17], s[36:37], 0, v[68:69]
	v_lshl_add_u64 v[70:71], v[16:17], 0, v[224:225]
	global_load_dwordx2 v[72:73], v[70:71], off
	global_load_dwordx4 v[20:23], v141, s[16:17]
	global_load_dwordx2 v[74:75], v[70:71], off offset:32
	global_load_dwordx4 v[24:27], v141, s[16:17] offset:64
	s_waitcnt lgkmcnt(0)
	v_mov_b32_e32 v16, v33
	v_mov_b32_e32 v17, v34
	v_mov_b32_e32 v33, v35
	v_pk_add_f32 v[16:17], v[16:17], v[32:33]
	global_load_dwordx2 v[76:77], v[70:71], off offset:64
	global_load_dwordx2 v[78:79], v[70:71], off offset:96
	global_load_dwordx2 v[80:81], v[70:71], off offset:512
	v_add_f32_e32 v16, v16, v17
	v_fmamk_f32 v16, v16, 0x3b000000, v245
	v_mul_f32_e32 v17, 0x4f800000, v16
	v_cmp_gt_f32_e32 vcc, s87, v16
	global_load_dwordx4 v[28:31], v141, s[16:17] offset:128
	global_load_dwordx4 v[32:35], v141, s[16:17] offset:192
	v_cndmask_b32_e32 v16, v16, v17, vcc
	v_sqrt_f32_e32 v17, v16
	v_lshl_add_u64 v[68:69], s[40:41], 0, v[68:69]
	v_add_u32_e32 v18, -1, v17
	v_fma_f32 v19, -v18, v17, v16
	v_cmp_ge_f32_e64 s[38:39], 0, v19
	v_add_u32_e32 v19, 1, v17
	s_waitcnt vmcnt(8)
	v_cvt_f32_f16_e32 v86, v72
	v_cndmask_b32_e64 v18, v17, v18, s[38:39]
	v_fma_f32 v17, -v19, v17, v16
	v_cmp_lt_f32_e64 s[38:39], 0, v17
	v_cvt_f32_f16_sdwa v87, v72 dst_sel:DWORD dst_unused:UNUSED_PAD src0_sel:WORD_1
	s_nop 0
	v_cndmask_b32_e64 v17, v18, v19, s[38:39]
	v_mul_f32_e32 v18, 0x37800000, v17
	v_cndmask_b32_e32 v17, v17, v18, vcc
	v_cmp_class_f32_e32 vcc, v16, v243
	s_nop 1
	v_cndmask_b32_e32 v17, v17, v16, vcc
	v_div_scale_f32 v18, s[2:3], v17, v17, 1.0
	v_rcp_f32_e32 v19, v18
	v_div_scale_f32 v40, vcc, 1.0, v17, 1.0
	v_mul_f32_e32 v16, 0x3b000000, v143
	v_fma_f32 v36, -v18, v19, 1.0
	v_fmac_f32_e32 v19, v36, v19
	global_load_dwordx4 v[36:39], v141, s[16:17] offset:1024
	v_mul_f32_e32 v41, v40, v19
	v_fma_f32 v42, -v18, v41, v40
	v_fmac_f32_e32 v41, v42, v19
	v_fma_f32 v18, -v18, v41, v40
	v_div_fmas_f32 v18, v18, v19, v41
	global_load_dwordx4 v[40:43], v141, s[16:17] offset:1088
	global_load_dwordx4 v[44:47], v141, s[16:17] offset:1152
	global_load_dwordx4 v[64:67], v141, s[16:17] offset:1216
	global_load_dwordx2 v[82:83], v[70:71], off offset:544
	global_load_dwordx2 v[84:85], v[70:71], off offset:576
	s_nop 0
	global_load_dwordx2 v[70:71], v[70:71], off offset:608
	v_div_fixup_f32 v18, v18, v17, 1.0
	v_pk_add_f32 v[8:9], v[8:9], v[16:17] op_sel_hi:[1,0] neg_lo:[0,1] neg_hi:[0,1]
	v_pk_add_f32 v[10:11], v[10:11], v[16:17] op_sel_hi:[1,0] neg_lo:[0,1] neg_hi:[0,1]
	v_pk_mul_f32 v[8:9], v[8:9], v[18:19] op_sel_hi:[1,0]
	v_pk_mul_f32 v[10:11], v[10:11], v[18:19] op_sel_hi:[1,0]
	s_waitcnt vmcnt(14)
	v_pk_mul_f32 v[8:9], v[8:9], v[20:21]
	v_cvt_f32_f16_e32 v20, v73
	v_cvt_f32_f16_sdwa v21, v73 dst_sel:DWORD dst_unused:UNUSED_PAD src0_sel:WORD_1
	v_pk_mul_f32 v[10:11], v[10:11], v[22:23]
	v_pk_mul_f32 v[8:9], v[8:9], v[86:87]
	v_pk_add_f32 v[0:1], v[0:1], v[16:17] op_sel_hi:[1,0] neg_lo:[0,1] neg_hi:[0,1]
	v_pk_mul_f32 v[10:11], v[10:11], v[20:21]
	v_cvt_pk_bf16_f32 v8, v8, v9
	v_cvt_pk_bf16_f32 v9, v10, v11
	v_lshl_add_u64 v[10:11], v[68:69], 0, v[224:225]
	global_store_dwordx2 v[10:11], v[8:9], off
	s_waitcnt vmcnt(14)
	v_cvt_f32_f16_e32 v8, v74
	v_cvt_f32_f16_sdwa v9, v74 dst_sel:DWORD dst_unused:UNUSED_PAD src0_sel:WORD_1
	v_pk_mul_f32 v[0:1], v[0:1], v[18:19] op_sel_hi:[1,0]
	v_pk_add_f32 v[2:3], v[2:3], v[16:17] op_sel_hi:[1,0] neg_lo:[0,1] neg_hi:[0,1]
	s_waitcnt vmcnt(13)
	v_pk_mul_f32 v[0:1], v[0:1], v[24:25]
	v_pk_mul_f32 v[2:3], v[2:3], v[18:19] op_sel_hi:[1,0]
	v_pk_mul_f32 v[0:1], v[0:1], v[8:9]
	v_cvt_f32_f16_e32 v8, v75
	v_cvt_f32_f16_sdwa v9, v75 dst_sel:DWORD dst_unused:UNUSED_PAD src0_sel:WORD_1
	v_pk_mul_f32 v[2:3], v[2:3], v[26:27]
	v_cvt_pk_bf16_f32 v0, v0, v1
	v_pk_mul_f32 v[2:3], v[2:3], v[8:9]
	s_nop 0
	v_cvt_pk_bf16_f32 v1, v2, v3
	global_store_dwordx2 v[10:11], v[0:1], off offset:32
	s_waitcnt vmcnt(13)
	v_cvt_f32_f16_e32 v0, v76
	v_cvt_f32_f16_sdwa v1, v76 dst_sel:DWORD dst_unused:UNUSED_PAD src0_sel:WORD_1
	v_pk_add_f32 v[2:3], v[4:5], v[16:17] op_sel_hi:[1,0] neg_lo:[0,1] neg_hi:[0,1]
	v_pk_add_f32 v[4:5], v[6:7], v[16:17] op_sel_hi:[1,0] neg_lo:[0,1] neg_hi:[0,1]
	v_pk_mul_f32 v[2:3], v[2:3], v[18:19] op_sel_hi:[1,0]
	v_pk_mul_f32 v[4:5], v[4:5], v[18:19] op_sel_hi:[1,0]
	s_waitcnt vmcnt(10)
	v_pk_mul_f32 v[2:3], v[2:3], v[28:29]
	v_pk_mul_f32 v[4:5], v[4:5], v[30:31]
	v_pk_mul_f32 v[0:1], v[2:3], v[0:1]
	v_cvt_f32_f16_e32 v2, v77
	v_cvt_f32_f16_sdwa v3, v77 dst_sel:DWORD dst_unused:UNUSED_PAD src0_sel:WORD_1
	v_cvt_pk_bf16_f32 v0, v0, v1
	v_pk_mul_f32 v[2:3], v[4:5], v[2:3]
	s_nop 0
	v_cvt_pk_bf16_f32 v1, v2, v3
	global_store_dwordx2 v[10:11], v[0:1], off offset:64
	v_cvt_f32_f16_e32 v0, v78
	v_cvt_f32_f16_sdwa v1, v78 dst_sel:DWORD dst_unused:UNUSED_PAD src0_sel:WORD_1
	v_pk_add_f32 v[2:3], v[12:13], v[16:17] op_sel_hi:[1,0] neg_lo:[0,1] neg_hi:[0,1]
	v_pk_add_f32 v[4:5], v[14:15], v[16:17] op_sel_hi:[1,0] neg_lo:[0,1] neg_hi:[0,1]
	v_pk_mul_f32 v[2:3], v[2:3], v[18:19] op_sel_hi:[1,0]
	v_pk_mul_f32 v[4:5], v[4:5], v[18:19] op_sel_hi:[1,0]
	s_waitcnt vmcnt(10)
	v_pk_mul_f32 v[2:3], v[2:3], v[32:33]
	v_pk_mul_f32 v[4:5], v[4:5], v[34:35]
	v_pk_mul_f32 v[0:1], v[2:3], v[0:1]
	v_cvt_f32_f16_e32 v2, v79
	v_cvt_f32_f16_sdwa v3, v79 dst_sel:DWORD dst_unused:UNUSED_PAD src0_sel:WORD_1
	v_cvt_pk_bf16_f32 v0, v0, v1
	v_pk_mul_f32 v[2:3], v[4:5], v[2:3]
	s_nop 0
	v_cvt_pk_bf16_f32 v1, v2, v3
	global_store_dwordx2 v[10:11], v[0:1], off offset:96
	v_cvt_f32_f16_e32 v0, v80
	v_cvt_f32_f16_sdwa v1, v80 dst_sel:DWORD dst_unused:UNUSED_PAD src0_sel:WORD_1
	v_pk_add_f32 v[2:3], v[60:61], v[16:17] op_sel_hi:[1,0] neg_lo:[0,1] neg_hi:[0,1]
	v_pk_add_f32 v[4:5], v[62:63], v[16:17] op_sel_hi:[1,0] neg_lo:[0,1] neg_hi:[0,1]
	v_pk_mul_f32 v[2:3], v[2:3], v[18:19] op_sel_hi:[1,0]
	v_pk_mul_f32 v[4:5], v[4:5], v[18:19] op_sel_hi:[1,0]
	s_waitcnt vmcnt(10)
	v_pk_mul_f32 v[2:3], v[2:3], v[36:37]
	s_nop 0
	v_pk_mul_f32 v[0:1], v[2:3], v[0:1]
	v_cvt_f32_f16_e32 v2, v81
	v_cvt_f32_f16_sdwa v3, v81 dst_sel:DWORD dst_unused:UNUSED_PAD src0_sel:WORD_1
	v_pk_mul_f32 v[4:5], v[4:5], v[38:39]
	v_cvt_pk_bf16_f32 v0, v0, v1
	v_pk_mul_f32 v[2:3], v[4:5], v[2:3]
	s_nop 0
	v_cvt_pk_bf16_f32 v1, v2, v3
	global_store_dwordx2 v[10:11], v[0:1], off offset:512
	s_waitcnt vmcnt(7)
	v_cvt_f32_f16_e32 v0, v82
	v_cvt_f32_f16_sdwa v1, v82 dst_sel:DWORD dst_unused:UNUSED_PAD src0_sel:WORD_1
	v_pk_add_f32 v[2:3], v[52:53], v[16:17] op_sel_hi:[1,0] neg_lo:[0,1] neg_hi:[0,1]
	v_pk_add_f32 v[4:5], v[54:55], v[16:17] op_sel_hi:[1,0] neg_lo:[0,1] neg_hi:[0,1]
	v_pk_mul_f32 v[2:3], v[2:3], v[18:19] op_sel_hi:[1,0]
	v_pk_mul_f32 v[4:5], v[4:5], v[18:19] op_sel_hi:[1,0]
	v_pk_mul_f32 v[2:3], v[2:3], v[40:41]
	v_pk_mul_f32 v[4:5], v[4:5], v[42:43]
	v_pk_mul_f32 v[0:1], v[2:3], v[0:1]
	v_cvt_f32_f16_e32 v2, v83
	v_cvt_f32_f16_sdwa v3, v83 dst_sel:DWORD dst_unused:UNUSED_PAD src0_sel:WORD_1
	v_cvt_pk_bf16_f32 v0, v0, v1
	v_pk_mul_f32 v[2:3], v[4:5], v[2:3]
	s_nop 0
	v_cvt_pk_bf16_f32 v1, v2, v3
	global_store_dwordx2 v[10:11], v[0:1], off offset:544
	s_waitcnt vmcnt(7)
	v_cvt_f32_f16_e32 v0, v84
	v_cvt_f32_f16_sdwa v1, v84 dst_sel:DWORD dst_unused:UNUSED_PAD src0_sel:WORD_1
	v_pk_add_f32 v[2:3], v[48:49], v[16:17] op_sel_hi:[1,0] neg_lo:[0,1] neg_hi:[0,1]
	v_pk_add_f32 v[4:5], v[50:51], v[16:17] op_sel_hi:[1,0] neg_lo:[0,1] neg_hi:[0,1]
	v_pk_mul_f32 v[2:3], v[2:3], v[18:19] op_sel_hi:[1,0]
	v_pk_mul_f32 v[4:5], v[4:5], v[18:19] op_sel_hi:[1,0]
	v_pk_mul_f32 v[2:3], v[2:3], v[44:45]
	v_pk_mul_f32 v[4:5], v[4:5], v[46:47]
	v_pk_mul_f32 v[0:1], v[2:3], v[0:1]
	v_cvt_f32_f16_e32 v2, v85
	v_cvt_f32_f16_sdwa v3, v85 dst_sel:DWORD dst_unused:UNUSED_PAD src0_sel:WORD_1
	v_cvt_pk_bf16_f32 v0, v0, v1
	v_pk_mul_f32 v[2:3], v[4:5], v[2:3]
	s_nop 0
	v_cvt_pk_bf16_f32 v1, v2, v3
	global_store_dwordx2 v[10:11], v[0:1], off offset:576
	s_waitcnt vmcnt(7)
	v_cvt_f32_f16_e32 v0, v70
	v_cvt_f32_f16_sdwa v1, v70 dst_sel:DWORD dst_unused:UNUSED_PAD src0_sel:WORD_1
	v_pk_add_f32 v[2:3], v[56:57], v[16:17] op_sel_hi:[1,0] neg_lo:[0,1] neg_hi:[0,1]
	v_pk_add_f32 v[4:5], v[58:59], v[16:17] op_sel_hi:[1,0] neg_lo:[0,1] neg_hi:[0,1]
	v_pk_mul_f32 v[2:3], v[2:3], v[18:19] op_sel_hi:[1,0]
	v_pk_mul_f32 v[4:5], v[4:5], v[18:19] op_sel_hi:[1,0]
	v_pk_mul_f32 v[2:3], v[2:3], v[64:65]
	v_pk_mul_f32 v[4:5], v[4:5], v[66:67]
	v_pk_mul_f32 v[0:1], v[2:3], v[0:1]
	v_cvt_f32_f16_e32 v2, v71
	v_cvt_f32_f16_sdwa v3, v71 dst_sel:DWORD dst_unused:UNUSED_PAD src0_sel:WORD_1
	v_cvt_pk_bf16_f32 v0, v0, v1
	v_pk_mul_f32 v[2:3], v[4:5], v[2:3]
	s_nop 0
	v_cvt_pk_bf16_f32 v1, v2, v3
	global_store_dwordx2 v[10:11], v[0:1], off offset:608
	s_cbranch_scc0 .LBB0_1817
